# GU epilogue: 8 serialized ssq row-scale loads issued together
# speedup vs baseline: 1.0147x; 1.0147x over previous
.LBB0_1106:
	s_lshl_b32 s0, s29, 8
	v_mov_b32_e32 v0, v193
	s_add_i32 s0, s0, s77
	v_pk_mul_f32 v[128:129], v[124:125], v[128:129]
	v_bfe_u32 v180, v0, 4, 2
	v_and_or_b32 v160, v0, 15, s0
	v_lshlrev_b32_e32 v0, 4, v180
	v_ashrrev_i32_e32 v161, 31, v160
	v_lshl_add_u64 v[130:131], s[10:11], 0, v[0:1]
	v_lshlrev_b64 v[132:133], 6, v[160:161]
	v_lshl_add_u64 v[132:133], v[130:131], 0, v[132:133]
	global_load_dwordx4 v[146:149], v[132:133], off
	global_load_dwordx4 v[186:189], v[132:133], off offset:1024
	global_load_dwordx4 v[214:217], v[132:133], off offset:2048
	global_load_dwordx4 v[228:231], v[132:133], off offset:3072
	v_add_co_u32_e32 v190, vcc, 0x2000, v132
	s_nop 1
	v_addc_co_u32_e32 v191, vcc, 0, v133, vcc
	global_load_dwordx4 v[232:235], v[190:191], off
	global_load_dwordx4 v[236:239], v[190:191], off offset:1024
	global_load_dwordx4 v[240:243], v[190:191], off offset:2048
	global_load_dwordx4 v[244:247], v[190:191], off offset:3072
	v_or_b32_e32 v158, 16, v160
	v_ashrrev_i32_e32 v159, 31, v158
	v_or_b32_e32 v156, 32, v160
	v_ashrrev_i32_e32 v157, 31, v156
	v_or_b32_e32 v154, 48, v160
	v_ashrrev_i32_e32 v155, 31, v154
	v_add_u32_e32 v152, 0x80, v160
	v_ashrrev_i32_e32 v153, 31, v152
	v_add_u32_e32 v150, 0x90, v160
	v_ashrrev_i32_e32 v151, 31, v150
	s_mov_b32 s0, 0x358637bd
	v_pk_mul_f32 v[120:121], v[116:117], v[120:121]
	v_pk_mul_f32 v[112:113], v[108:109], v[112:113]
	v_pk_mul_f32 v[104:105], v[100:101], v[104:105]
	v_pk_mul_f32 v[96:97], v[92:93], v[96:97]
	v_pk_mul_f32 v[88:89], v[84:85], v[88:89]
	v_pk_mul_f32 v[80:81], v[76:77], v[80:81]
	v_pk_mul_f32 v[72:73], v[68:69], v[72:73]
	v_pk_mul_f32 v[64:65], v[60:61], v[64:65]
	v_pk_mul_f32 v[56:57], v[52:53], v[56:57]
	v_pk_mul_f32 v[48:49], v[44:45], v[48:49]
	v_pk_mul_f32 v[40:41], v[36:37], v[40:41]
	v_pk_mul_f32 v[32:33], v[28:29], v[32:33]
	v_pk_mul_f32 v[24:25], v[20:21], v[24:25]
	v_pk_mul_f32 v[16:17], v[12:13], v[16:17]
	v_pk_mul_f32 v[2:3], v[6:7], v[2:3]
	v_pk_mul_f32 v[4:5], v[8:9], v[4:5]
	s_waitcnt vmcnt(0) lgkmcnt(0)
	v_mov_b32_e32 v132, v147
	v_mov_b32_e32 v133, v148
	v_mov_b32_e32 v147, v149
	v_pk_add_f32 v[132:133], v[132:133], v[146:147]
	s_nop 0
	v_add_f32_e32 v0, v132, v133
	ds_swizzle_b32 v132, v0 offset:swizzle(SWAP,16)
	s_waitcnt lgkmcnt(0)
	v_add_f32_e32 v163, v0, v132
	v_mov_b32_e32 v165, v163
	s_nop 1
	v_permlane32_swap_b32_e32 v163, v165
	s_waitcnt vmcnt(0) lgkmcnt(0)
	v_mov_b32_e32 v132, v187
	v_mov_b32_e32 v133, v188
	v_mov_b32_e32 v187, v189
	v_pk_add_f32 v[132:133], v[132:133], v[186:187]
	s_nop 0
	v_add_f32_e32 v0, v132, v133
	ds_swizzle_b32 v132, v0 offset:swizzle(SWAP,16)
	s_waitcnt lgkmcnt(0)
	v_add_f32_e32 v166, v0, v132
	v_mov_b32_e32 v168, v166
	s_nop 1
	v_permlane32_swap_b32_e32 v166, v168
	s_waitcnt vmcnt(0) lgkmcnt(0)
	v_mov_b32_e32 v132, v215
	v_mov_b32_e32 v133, v216
	v_mov_b32_e32 v215, v217
	v_pk_add_f32 v[132:133], v[132:133], v[214:215]
	s_nop 0
	v_add_f32_e32 v0, v132, v133
	ds_swizzle_b32 v132, v0 offset:swizzle(SWAP,16)
	s_waitcnt lgkmcnt(0)
	v_add_f32_e32 v167, v0, v132
	v_mov_b32_e32 v169, v167
	s_nop 1
	v_permlane32_swap_b32_e32 v167, v169
	v_pk_add_f32 v[166:167], v[166:167], v[168:169]
	s_waitcnt vmcnt(0) lgkmcnt(0)
	v_mov_b32_e32 v132, v229
	v_mov_b32_e32 v133, v230
	v_mov_b32_e32 v229, v231
	v_pk_add_f32 v[132:133], v[132:133], v[228:229]
	s_nop 0
	v_add_f32_e32 v0, v132, v133
	ds_swizzle_b32 v132, v0 offset:swizzle(SWAP,16)
	s_waitcnt lgkmcnt(0)
	v_add_f32_e32 v170, v0, v132
	v_mov_b32_e32 v172, v170
	s_nop 1
	v_permlane32_swap_b32_e32 v170, v172
	s_waitcnt vmcnt(0) lgkmcnt(0)
	v_mov_b32_e32 v132, v233
	v_mov_b32_e32 v133, v234
	v_mov_b32_e32 v233, v235
	v_pk_add_f32 v[132:133], v[132:133], v[232:233]
	s_nop 0
	v_add_f32_e32 v0, v132, v133
	ds_swizzle_b32 v132, v0 offset:swizzle(SWAP,16)
	s_waitcnt lgkmcnt(0)
	v_add_f32_e32 v171, v0, v132
	v_mov_b32_e32 v173, v171
	s_nop 1
	v_permlane32_swap_b32_e32 v171, v173
	v_pk_add_f32 v[170:171], v[170:171], v[172:173]
	s_waitcnt vmcnt(0) lgkmcnt(0)
	v_mov_b32_e32 v132, v237
	v_mov_b32_e32 v133, v238
	v_mov_b32_e32 v237, v239
	v_pk_add_f32 v[132:133], v[132:133], v[236:237]
	v_add_u32_e32 v148, 0xa0, v160
	v_add_f32_e32 v0, v132, v133
	ds_swizzle_b32 v132, v0 offset:swizzle(SWAP,16)
	v_ashrrev_i32_e32 v149, 31, v148
	v_add_u32_e32 v146, 0xb0, v160
	v_ashrrev_i32_e32 v147, 31, v146
	s_waitcnt lgkmcnt(0)
	v_add_f32_e32 v174, v0, v132
	v_mov_b32_e32 v176, v174
	s_nop 1
	v_permlane32_swap_b32_e32 v174, v176
	s_waitcnt vmcnt(0) lgkmcnt(0)
	v_mov_b32_e32 v132, v241
	v_mov_b32_e32 v133, v242
	v_mov_b32_e32 v241, v243
	v_pk_add_f32 v[132:133], v[132:133], v[240:241]
	s_nop 0
	v_add_f32_e32 v0, v132, v133
	ds_swizzle_b32 v132, v0 offset:swizzle(SWAP,16)
	s_waitcnt lgkmcnt(0)
	v_add_f32_e32 v175, v0, v132
	v_mov_b32_e32 v177, v175
	s_nop 1
	v_permlane32_swap_b32_e32 v175, v177
	v_pk_add_f32 v[174:175], v[174:175], v[176:177]
	v_mov_b64_e32 v[176:177], s[0:1]
	v_pk_fma_f32 v[174:175], v[174:175], s[62:63], v[176:177] op_sel_hi:[1,0,0]
	v_pk_fma_f32 v[170:171], v[170:171], s[62:63], v[176:177] op_sel_hi:[1,0,0]
	v_mul_f32_e32 v0, 0x4b800000, v175
	v_cmp_gt_f32_e64 s[2:3], s60, v175
	v_cmp_gt_f32_e32 vcc, s60, v174
	v_pk_fma_f32 v[166:167], v[166:167], s[62:63], v[176:177] op_sel_hi:[1,0,0]
	v_cndmask_b32_e64 v0, v175, v0, s[2:3]
	v_rsq_f32_e32 v0, v0
	s_lshl_b32 s0, s28, 7
	v_mul_f32_e32 v147, 0x45800000, v0
	v_cndmask_b32_e64 v147, v0, v147, s[2:3]
	v_mul_f32_e32 v0, 0x4b800000, v174
	v_cndmask_b32_e32 v0, v174, v0, vcc
	v_rsq_f32_e32 v0, v0
	v_cmp_gt_f32_e64 s[2:3], s60, v171
	v_mul_f32_e32 v149, 0x45800000, v0
	v_cndmask_b32_e32 v149, v0, v149, vcc
	v_mul_f32_e32 v0, 0x4b800000, v171
	v_cndmask_b32_e64 v0, v171, v0, s[2:3]
	v_rsq_f32_e32 v0, v0
	v_cmp_gt_f32_e32 vcc, s60, v170
	v_mul_f32_e32 v151, 0x45800000, v0
	v_cndmask_b32_e64 v151, v0, v151, s[2:3]
	v_mul_f32_e32 v0, 0x4b800000, v170
	v_cndmask_b32_e32 v0, v170, v0, vcc
	v_rsq_f32_e32 v0, v0
	v_cmp_gt_f32_e64 s[2:3], s60, v167
	v_mul_f32_e32 v153, 0x45800000, v0
	v_cndmask_b32_e32 v153, v0, v153, vcc
	v_mul_f32_e32 v0, 0x4b800000, v167
	v_cndmask_b32_e64 v0, v167, v0, s[2:3]
	v_rsq_f32_e32 v0, v0
	v_cmp_gt_f32_e32 vcc, s60, v166
	v_mul_f32_e32 v155, 0x45800000, v0
	v_cndmask_b32_e64 v155, v0, v155, s[2:3]
	v_mul_f32_e32 v0, 0x4b800000, v166
	v_cndmask_b32_e32 v0, v166, v0, vcc
	v_rsq_f32_e32 v0, v0
	s_waitcnt vmcnt(0) lgkmcnt(0)
	v_mov_b32_e32 v166, v245
	v_mov_b32_e32 v167, v246
	v_mov_b32_e32 v245, v247
	v_mul_f32_e32 v157, 0x45800000, v0
	v_pk_add_f32 v[130:131], v[166:167], v[244:245]
	v_cndmask_b32_e32 v157, v0, v157, vcc
	v_add_f32_e32 v0, v130, v131
	ds_swizzle_b32 v130, v0 offset:swizzle(SWAP,16)
	s_waitcnt lgkmcnt(0)
	v_add_f32_e32 v162, v0, v130
	v_mov_b32_e32 v164, v162
	s_nop 1
	v_permlane32_swap_b32_e32 v162, v164
	v_pk_add_f32 v[130:131], v[162:163], v[164:165]
	s_nop 0
	v_pk_fma_f32 v[130:131], v[130:131], s[62:63], v[176:177] op_sel_hi:[1,0,0]
	s_nop 0
	v_mul_f32_e32 v0, 0x4b800000, v131
	v_cmp_gt_f32_e64 s[2:3], s60, v131
	v_cmp_gt_f32_e32 vcc, s60, v130
	s_nop 0
	v_cndmask_b32_e64 v0, v131, v0, s[2:3]
	v_rsq_f32_e32 v0, v0
	s_nop 0
	v_mul_f32_e32 v131, 0x45800000, v0
	v_cndmask_b32_e64 v159, v0, v131, s[2:3]
	v_mul_f32_e32 v163, 0xbfb8aa3b, v159
	v_mul_f32_e32 v162, v159, v159
	v_mul_f32_e32 v159, v122, v163
	v_exp_f32_e32 v159, v159
	v_mul_f32_e32 v0, 0x4b800000, v130
	v_cndmask_b32_e32 v0, v130, v0, vcc
	v_rsq_f32_e32 v0, v0
	v_add_f32_e32 v159, 1.0, v159
	v_rcp_f32_e32 v164, v159
	v_mul_f32_e32 v159, v123, v163
	v_exp_f32_e32 v159, v159
	v_pk_mul_f32 v[122:123], v[122:123], v[126:127]
	v_mul_f32_e32 v130, 0x45800000, v0
	v_cndmask_b32_e32 v0, v0, v130, vcc
	v_add_f32_e32 v159, 1.0, v159
	v_rcp_f32_e32 v165, v159
	v_lshl_or_b32 v130, v180, 3, s0
	v_or_b32_e32 v132, s78, v130
	v_ashrrev_i32_e32 v133, 31, v132
	v_pk_mul_f32 v[126:127], v[162:163], v[164:165] op_sel_hi:[0,1]
	v_pk_mul_f32 v[122:123], v[122:123], v[126:127]
	v_mov_b64_e32 v[130:131], s[8:9]
	v_cvt_pk_bf16_f32 v122, v122, v123
	v_mul_f32_e32 v123, v124, v163
	v_exp_f32_e32 v123, v123
	v_mad_i64_i32 v[160:161], s[2:3], v160, s70, v[130:131]
	v_lshlrev_b64 v[132:133], 1, v[132:133]
	v_add_f32_e32 v123, 1.0, v123
	v_rcp_f32_e32 v124, v123
	v_mul_f32_e32 v123, v125, v163
	v_exp_f32_e32 v123, v123
	v_lshl_add_u64 v[160:161], v[160:161], 0, v[132:133]
	s_andn2_b64 vcc, exec, s[38:39]
	v_add_f32_e32 v123, 1.0, v123
	v_rcp_f32_e32 v125, v123
	s_nop 0
	v_pk_mul_f32 v[124:125], v[162:163], v[124:125] op_sel_hi:[0,1]
	v_pk_mul_f32 v[124:125], v[128:129], v[124:125]
	s_nop 0
	v_cvt_pk_bf16_f32 v123, v124, v125
	v_mul_f32_e32 v124, v114, v163
	v_mul_f32_e32 v125, v115, v163
	v_exp_f32_e32 v124, v124
	v_exp_f32_e32 v125, v125
	v_pk_mul_f32 v[114:115], v[114:115], v[118:119]
	v_add_f32_e32 v124, 1.0, v124
	v_add_f32_e32 v125, 1.0, v125
	v_rcp_f32_e32 v124, v124
	v_rcp_f32_e32 v125, v125
	s_nop 0
	v_pk_mul_f32 v[118:119], v[162:163], v[124:125] op_sel_hi:[0,1]
	v_pk_mul_f32 v[114:115], v[114:115], v[118:119]
	s_nop 0
	v_cvt_pk_bf16_f32 v124, v114, v115
	v_mul_f32_e32 v115, v117, v163
	v_mul_f32_e32 v117, 0xbfb8aa3b, v157
	v_mul_f32_e32 v118, v106, v117
	v_mul_f32_e32 v119, v107, v117
	v_exp_f32_e32 v118, v118
	v_exp_f32_e32 v119, v119
	v_mul_f32_e32 v114, v116, v163
	v_mul_f32_e32 v116, v157, v157
	v_add_f32_e32 v118, 1.0, v118
	v_add_f32_e32 v119, 1.0, v119
	v_rcp_f32_e32 v118, v118
	v_rcp_f32_e32 v119, v119
	v_pk_mul_f32 v[106:107], v[106:107], v[110:111]
	v_exp_f32_e32 v114, v114
	v_exp_f32_e32 v115, v115
	v_pk_mul_f32 v[110:111], v[116:117], v[118:119] op_sel_hi:[0,1]
	v_pk_mul_f32 v[106:107], v[106:107], v[110:111]
	v_add_f32_e32 v114, 1.0, v114
	v_cvt_pk_bf16_f32 v106, v106, v107
	v_mul_f32_e32 v107, v108, v117
	v_exp_f32_e32 v107, v107
	v_add_f32_e32 v115, 1.0, v115
	v_rcp_f32_e32 v114, v114
	v_rcp_f32_e32 v115, v115
	v_add_f32_e32 v107, 1.0, v107
	v_rcp_f32_e32 v108, v107
	v_mul_f32_e32 v107, v109, v117
	v_exp_f32_e32 v107, v107
	v_pk_mul_f32 v[114:115], v[162:163], v[114:115] op_sel_hi:[0,1]
	v_pk_mul_f32 v[114:115], v[120:121], v[114:115]
	v_add_f32_e32 v107, 1.0, v107
	v_rcp_f32_e32 v109, v107
	v_cvt_pk_bf16_f32 v125, v114, v115
	v_mad_i64_i32 v[114:115], s[2:3], v158, s70, v[130:131]
	v_pk_mul_f32 v[108:109], v[116:117], v[108:109] op_sel_hi:[0,1]
	v_pk_mul_f32 v[108:109], v[112:113], v[108:109]
	v_lshl_add_u64 v[114:115], v[114:115], 0, v[132:133]
	v_cvt_pk_bf16_f32 v107, v108, v109
	v_mul_f32_e32 v108, v98, v117
	v_mul_f32_e32 v109, v99, v117
	v_exp_f32_e32 v108, v108
	v_exp_f32_e32 v109, v109
	v_pk_mul_f32 v[98:99], v[98:99], v[102:103]
	flat_store_dwordx4 v[160:161], v[122:125]
	v_add_f32_e32 v108, 1.0, v108
	v_add_f32_e32 v109, 1.0, v109
	v_rcp_f32_e32 v108, v108
	v_rcp_f32_e32 v109, v109
	s_nop 0
	v_pk_mul_f32 v[102:103], v[116:117], v[108:109] op_sel_hi:[0,1]
	v_pk_mul_f32 v[98:99], v[98:99], v[102:103]
	s_nop 0
	v_cvt_pk_bf16_f32 v108, v98, v99
	v_mul_f32_e32 v99, v101, v117
	v_mul_f32_e32 v101, 0xbfb8aa3b, v155
	v_mul_f32_e32 v102, v90, v101
	v_mul_f32_e32 v103, v91, v101
	v_exp_f32_e32 v102, v102
	v_exp_f32_e32 v103, v103
	v_mul_f32_e32 v98, v100, v117
	v_mul_f32_e32 v100, v155, v155
	v_add_f32_e32 v102, 1.0, v102
	v_add_f32_e32 v103, 1.0, v103
	v_rcp_f32_e32 v102, v102
	v_rcp_f32_e32 v103, v103
	v_pk_mul_f32 v[90:91], v[90:91], v[94:95]
	v_exp_f32_e32 v98, v98
	v_exp_f32_e32 v99, v99
	v_pk_mul_f32 v[94:95], v[100:101], v[102:103] op_sel_hi:[0,1]
	v_pk_mul_f32 v[90:91], v[90:91], v[94:95]
	v_add_f32_e32 v98, 1.0, v98
	v_cvt_pk_bf16_f32 v90, v90, v91
	v_mul_f32_e32 v91, v92, v101
	v_exp_f32_e32 v91, v91
	v_add_f32_e32 v99, 1.0, v99
	v_rcp_f32_e32 v98, v98
	v_rcp_f32_e32 v99, v99
	v_add_f32_e32 v91, 1.0, v91
	v_rcp_f32_e32 v92, v91
	v_mul_f32_e32 v91, v93, v101
	v_exp_f32_e32 v91, v91
	v_pk_mul_f32 v[98:99], v[116:117], v[98:99] op_sel_hi:[0,1]
	v_pk_mul_f32 v[98:99], v[104:105], v[98:99]
	v_add_f32_e32 v91, 1.0, v91
	v_rcp_f32_e32 v93, v91
	v_cvt_pk_bf16_f32 v109, v98, v99
	v_mad_i64_i32 v[98:99], s[2:3], v156, s70, v[130:131]
	v_pk_mul_f32 v[92:93], v[100:101], v[92:93] op_sel_hi:[0,1]
	v_pk_mul_f32 v[92:93], v[96:97], v[92:93]
	v_lshl_add_u64 v[98:99], v[98:99], 0, v[132:133]
	v_cvt_pk_bf16_f32 v91, v92, v93
	v_mul_f32_e32 v92, v82, v101
	v_mul_f32_e32 v93, v83, v101
	v_exp_f32_e32 v92, v92
	v_exp_f32_e32 v93, v93
	v_pk_mul_f32 v[82:83], v[82:83], v[86:87]
	flat_store_dwordx4 v[114:115], v[106:109]
	v_add_f32_e32 v92, 1.0, v92
	v_add_f32_e32 v93, 1.0, v93
	v_rcp_f32_e32 v92, v92
	v_rcp_f32_e32 v93, v93
	s_nop 0
	v_pk_mul_f32 v[86:87], v[100:101], v[92:93] op_sel_hi:[0,1]
	v_pk_mul_f32 v[82:83], v[82:83], v[86:87]
	s_nop 0
	v_cvt_pk_bf16_f32 v92, v82, v83
	v_mul_f32_e32 v83, v85, v101
	v_mul_f32_e32 v85, 0xbfb8aa3b, v153
	v_mul_f32_e32 v86, v74, v85
	v_mul_f32_e32 v87, v75, v85
	v_exp_f32_e32 v86, v86
	v_exp_f32_e32 v87, v87
	v_mul_f32_e32 v82, v84, v101
	v_mul_f32_e32 v84, v153, v153
	v_add_f32_e32 v86, 1.0, v86
	v_add_f32_e32 v87, 1.0, v87
	v_rcp_f32_e32 v86, v86
	v_rcp_f32_e32 v87, v87
	v_pk_mul_f32 v[74:75], v[74:75], v[78:79]
	v_exp_f32_e32 v82, v82
	v_exp_f32_e32 v83, v83
	v_pk_mul_f32 v[78:79], v[84:85], v[86:87] op_sel_hi:[0,1]
	v_pk_mul_f32 v[74:75], v[74:75], v[78:79]
	v_add_f32_e32 v82, 1.0, v82
	v_cvt_pk_bf16_f32 v74, v74, v75
	v_mul_f32_e32 v75, v76, v85
	v_exp_f32_e32 v75, v75
	v_add_f32_e32 v83, 1.0, v83
	v_rcp_f32_e32 v82, v82
	v_rcp_f32_e32 v83, v83
	v_add_f32_e32 v75, 1.0, v75
	v_rcp_f32_e32 v76, v75
	v_mul_f32_e32 v75, v77, v85
	v_exp_f32_e32 v75, v75
	v_pk_mul_f32 v[82:83], v[100:101], v[82:83] op_sel_hi:[0,1]
	v_pk_mul_f32 v[82:83], v[88:89], v[82:83]
	v_add_f32_e32 v75, 1.0, v75
	v_rcp_f32_e32 v77, v75
	v_cvt_pk_bf16_f32 v93, v82, v83
	v_mad_i64_i32 v[82:83], s[2:3], v154, s70, v[130:131]
	v_pk_mul_f32 v[76:77], v[84:85], v[76:77] op_sel_hi:[0,1]
	v_pk_mul_f32 v[76:77], v[80:81], v[76:77]
	v_lshl_add_u64 v[82:83], v[82:83], 0, v[132:133]
	v_cvt_pk_bf16_f32 v75, v76, v77
	v_mul_f32_e32 v76, v66, v85
	v_mul_f32_e32 v77, v67, v85
	v_exp_f32_e32 v76, v76
	v_exp_f32_e32 v77, v77
	v_pk_mul_f32 v[66:67], v[66:67], v[70:71]
	flat_store_dwordx4 v[98:99], v[90:93]
	v_add_f32_e32 v76, 1.0, v76
	v_add_f32_e32 v77, 1.0, v77
	v_rcp_f32_e32 v76, v76
	v_rcp_f32_e32 v77, v77
	s_nop 0
	v_pk_mul_f32 v[70:71], v[84:85], v[76:77] op_sel_hi:[0,1]
	v_pk_mul_f32 v[66:67], v[66:67], v[70:71]
	s_nop 0
	v_cvt_pk_bf16_f32 v76, v66, v67
	v_mul_f32_e32 v67, v69, v85
	v_mul_f32_e32 v69, 0xbfb8aa3b, v151
	v_mul_f32_e32 v70, v58, v69
	v_mul_f32_e32 v71, v59, v69
	v_exp_f32_e32 v70, v70
	v_exp_f32_e32 v71, v71
	v_mul_f32_e32 v66, v68, v85
	v_mul_f32_e32 v68, v151, v151
	v_add_f32_e32 v70, 1.0, v70
	v_add_f32_e32 v71, 1.0, v71
	v_rcp_f32_e32 v70, v70
	v_rcp_f32_e32 v71, v71
	v_pk_mul_f32 v[58:59], v[58:59], v[62:63]
	v_exp_f32_e32 v66, v66
	v_exp_f32_e32 v67, v67
	v_pk_mul_f32 v[62:63], v[68:69], v[70:71] op_sel_hi:[0,1]
	v_pk_mul_f32 v[58:59], v[58:59], v[62:63]
	v_add_f32_e32 v66, 1.0, v66
	v_cvt_pk_bf16_f32 v58, v58, v59
	v_mul_f32_e32 v59, v60, v69
	v_exp_f32_e32 v59, v59
	v_add_f32_e32 v67, 1.0, v67
	v_rcp_f32_e32 v66, v66
	v_rcp_f32_e32 v67, v67
	v_add_f32_e32 v59, 1.0, v59
	v_rcp_f32_e32 v60, v59
	v_mul_f32_e32 v59, v61, v69
	v_exp_f32_e32 v59, v59
	v_pk_mul_f32 v[66:67], v[84:85], v[66:67] op_sel_hi:[0,1]
	v_pk_mul_f32 v[66:67], v[72:73], v[66:67]
	v_add_f32_e32 v59, 1.0, v59
	v_rcp_f32_e32 v61, v59
	v_cvt_pk_bf16_f32 v77, v66, v67
	v_mad_i64_i32 v[66:67], s[2:3], v152, s70, v[130:131]
	v_pk_mul_f32 v[60:61], v[68:69], v[60:61] op_sel_hi:[0,1]
	v_pk_mul_f32 v[60:61], v[64:65], v[60:61]
	v_lshl_add_u64 v[66:67], v[66:67], 0, v[132:133]
	v_cvt_pk_bf16_f32 v59, v60, v61
	v_mul_f32_e32 v60, v50, v69
	v_mul_f32_e32 v61, v51, v69
	v_exp_f32_e32 v60, v60
	v_exp_f32_e32 v61, v61
	v_pk_mul_f32 v[50:51], v[50:51], v[54:55]
	flat_store_dwordx4 v[82:83], v[74:77]
	v_add_f32_e32 v60, 1.0, v60
	v_add_f32_e32 v61, 1.0, v61
	v_rcp_f32_e32 v60, v60
	v_rcp_f32_e32 v61, v61
	s_nop 0
	v_pk_mul_f32 v[54:55], v[68:69], v[60:61] op_sel_hi:[0,1]
	v_pk_mul_f32 v[50:51], v[50:51], v[54:55]
	s_nop 0
	v_cvt_pk_bf16_f32 v60, v50, v51
	v_mul_f32_e32 v51, v53, v69
	v_mul_f32_e32 v53, 0xbfb8aa3b, v149
	v_mul_f32_e32 v54, v42, v53
	v_mul_f32_e32 v55, v43, v53
	v_exp_f32_e32 v54, v54
	v_exp_f32_e32 v55, v55
	v_mul_f32_e32 v50, v52, v69
	v_mul_f32_e32 v52, v149, v149
	v_add_f32_e32 v54, 1.0, v54
	v_add_f32_e32 v55, 1.0, v55
	v_rcp_f32_e32 v54, v54
	v_rcp_f32_e32 v55, v55
	v_pk_mul_f32 v[42:43], v[42:43], v[46:47]
	v_exp_f32_e32 v50, v50
	v_exp_f32_e32 v51, v51
	v_pk_mul_f32 v[46:47], v[52:53], v[54:55] op_sel_hi:[0,1]
	v_pk_mul_f32 v[42:43], v[42:43], v[46:47]
	v_add_f32_e32 v50, 1.0, v50
	v_cvt_pk_bf16_f32 v42, v42, v43
	v_mul_f32_e32 v43, v44, v53
	v_exp_f32_e32 v43, v43
	v_add_f32_e32 v51, 1.0, v51
	v_rcp_f32_e32 v50, v50
	v_rcp_f32_e32 v51, v51
	v_add_f32_e32 v43, 1.0, v43
	v_rcp_f32_e32 v44, v43
	v_mul_f32_e32 v43, v45, v53
	v_exp_f32_e32 v43, v43
	v_pk_mul_f32 v[50:51], v[68:69], v[50:51] op_sel_hi:[0,1]
	v_pk_mul_f32 v[50:51], v[56:57], v[50:51]
	v_add_f32_e32 v43, 1.0, v43
	v_rcp_f32_e32 v45, v43
	v_cvt_pk_bf16_f32 v61, v50, v51
	v_mad_i64_i32 v[50:51], s[2:3], v150, s70, v[130:131]
	v_pk_mul_f32 v[44:45], v[52:53], v[44:45] op_sel_hi:[0,1]
	v_pk_mul_f32 v[44:45], v[48:49], v[44:45]
	v_lshl_add_u64 v[50:51], v[50:51], 0, v[132:133]
	v_cvt_pk_bf16_f32 v43, v44, v45
	v_mul_f32_e32 v44, v34, v53
	v_mul_f32_e32 v45, v35, v53
	v_exp_f32_e32 v44, v44
	v_exp_f32_e32 v45, v45
	v_pk_mul_f32 v[34:35], v[34:35], v[38:39]
	flat_store_dwordx4 v[66:67], v[58:61]
	v_add_f32_e32 v44, 1.0, v44
	v_add_f32_e32 v45, 1.0, v45
	v_rcp_f32_e32 v44, v44
	v_rcp_f32_e32 v45, v45
	s_nop 0
	v_pk_mul_f32 v[38:39], v[52:53], v[44:45] op_sel_hi:[0,1]
	v_pk_mul_f32 v[34:35], v[34:35], v[38:39]
	s_nop 0
	v_cvt_pk_bf16_f32 v44, v34, v35
	v_mul_f32_e32 v35, v37, v53
	v_mul_f32_e32 v37, 0xbfb8aa3b, v147
	v_mul_f32_e32 v38, v26, v37
	v_mul_f32_e32 v39, v27, v37
	v_exp_f32_e32 v38, v38
	v_exp_f32_e32 v39, v39
	v_mul_f32_e32 v34, v36, v53
	v_mul_f32_e32 v36, v147, v147
	v_add_f32_e32 v38, 1.0, v38
	v_add_f32_e32 v39, 1.0, v39
	v_rcp_f32_e32 v38, v38
	v_rcp_f32_e32 v39, v39
	v_pk_mul_f32 v[26:27], v[26:27], v[30:31]
	v_exp_f32_e32 v34, v34
	v_exp_f32_e32 v35, v35
	v_pk_mul_f32 v[30:31], v[36:37], v[38:39] op_sel_hi:[0,1]
	v_pk_mul_f32 v[26:27], v[26:27], v[30:31]
	v_add_f32_e32 v34, 1.0, v34
	v_cvt_pk_bf16_f32 v26, v26, v27
	v_mul_f32_e32 v27, v28, v37
	v_exp_f32_e32 v27, v27
	v_add_f32_e32 v35, 1.0, v35
	v_rcp_f32_e32 v34, v34
	v_rcp_f32_e32 v35, v35
	v_add_f32_e32 v27, 1.0, v27
	v_rcp_f32_e32 v28, v27
	v_mul_f32_e32 v27, v29, v37
	v_exp_f32_e32 v27, v27
	v_pk_mul_f32 v[34:35], v[52:53], v[34:35] op_sel_hi:[0,1]
	v_pk_mul_f32 v[34:35], v[40:41], v[34:35]
	v_add_f32_e32 v27, 1.0, v27
	v_rcp_f32_e32 v29, v27
	v_cvt_pk_bf16_f32 v45, v34, v35
	v_mad_i64_i32 v[34:35], s[2:3], v148, s70, v[130:131]
	v_pk_mul_f32 v[28:29], v[36:37], v[28:29] op_sel_hi:[0,1]
	v_pk_mul_f32 v[28:29], v[32:33], v[28:29]
	v_lshl_add_u64 v[34:35], v[34:35], 0, v[132:133]
	v_cvt_pk_bf16_f32 v27, v28, v29
	v_mul_f32_e32 v28, v18, v37
	v_mul_f32_e32 v29, v19, v37
	v_exp_f32_e32 v28, v28
	v_exp_f32_e32 v29, v29
	v_pk_mul_f32 v[18:19], v[18:19], v[22:23]
	flat_store_dwordx4 v[50:51], v[42:45]
	v_add_f32_e32 v28, 1.0, v28
	v_add_f32_e32 v29, 1.0, v29
	v_rcp_f32_e32 v28, v28
	v_rcp_f32_e32 v29, v29
	s_nop 0
	v_pk_mul_f32 v[22:23], v[36:37], v[28:29] op_sel_hi:[0,1]
	v_pk_mul_f32 v[18:19], v[18:19], v[22:23]
	v_mul_f32_e32 v22, 0xbfb8aa3b, v0
	v_cvt_pk_bf16_f32 v28, v18, v19
	v_mul_f32_e32 v18, v20, v37
	v_mul_f32_e32 v19, v21, v37
	v_mul_f32_e32 v20, v10, v22
	v_mul_f32_e32 v21, v11, v22
	v_exp_f32_e32 v20, v20
	v_exp_f32_e32 v21, v21
	v_mul_f32_e32 v0, v0, v0
	v_pk_mul_f32 v[10:11], v[10:11], v[14:15]
	v_add_f32_e32 v20, 1.0, v20
	v_add_f32_e32 v21, 1.0, v21
	v_rcp_f32_e32 v20, v20
	v_rcp_f32_e32 v21, v21
	v_exp_f32_e32 v18, v18
	v_exp_f32_e32 v19, v19
	v_pk_mul_f32 v[14:15], v[0:1], v[20:21] op_sel_hi:[0,1]
	v_pk_mul_f32 v[10:11], v[10:11], v[14:15]
	v_add_f32_e32 v18, 1.0, v18
	v_cvt_pk_bf16_f32 v10, v10, v11
	v_mul_f32_e32 v11, v12, v22
	v_exp_f32_e32 v11, v11
	v_add_f32_e32 v19, 1.0, v19
	v_rcp_f32_e32 v18, v18
	v_rcp_f32_e32 v19, v19
	v_add_f32_e32 v11, 1.0, v11
	v_rcp_f32_e32 v12, v11
	v_mul_f32_e32 v11, v13, v22
	v_exp_f32_e32 v11, v11
	v_pk_mul_f32 v[18:19], v[36:37], v[18:19] op_sel_hi:[0,1]
	v_pk_mul_f32 v[18:19], v[24:25], v[18:19]
	v_add_f32_e32 v11, 1.0, v11
	v_rcp_f32_e32 v13, v11
	v_cvt_pk_bf16_f32 v29, v18, v19
	v_mad_i64_i32 v[18:19], s[2:3], v146, s70, v[130:131]
	v_pk_mul_f32 v[12:13], v[0:1], v[12:13] op_sel_hi:[0,1]
	v_pk_mul_f32 v[12:13], v[16:17], v[12:13]
	v_lshl_add_u64 v[18:19], v[18:19], 0, v[132:133]
	v_cvt_pk_bf16_f32 v11, v12, v13
	v_mul_f32_e32 v12, v6, v22
	v_mul_f32_e32 v13, v7, v22
	v_exp_f32_e32 v12, v12
	v_exp_f32_e32 v13, v13
	s_mov_b64 s[2:3], -1
	flat_store_dwordx4 v[34:35], v[26:29]
	v_add_f32_e32 v12, 1.0, v12
	v_add_f32_e32 v13, 1.0, v13
	v_rcp_f32_e32 v12, v12
	v_rcp_f32_e32 v13, v13
	s_nop 0
	v_pk_mul_f32 v[6:7], v[0:1], v[12:13] op_sel_hi:[0,1]
	v_pk_mul_f32 v[2:3], v[2:3], v[6:7]
	s_nop 0
	v_cvt_pk_bf16_f32 v12, v2, v3
	v_mul_f32_e32 v2, v8, v22
	v_mul_f32_e32 v3, v9, v22
	v_exp_f32_e32 v2, v2
	v_exp_f32_e32 v3, v3
	v_add_f32_e32 v2, 1.0, v2
	v_add_f32_e32 v3, 1.0, v3
	v_rcp_f32_e32 v2, v2
	v_rcp_f32_e32 v3, v3
	s_nop 0
	v_pk_mul_f32 v[2:3], v[0:1], v[2:3] op_sel_hi:[0,1]
	v_pk_mul_f32 v[2:3], v[4:5], v[2:3]
	s_nop 0
	v_cvt_pk_bf16_f32 v13, v2, v3
	flat_store_dwordx4 v[18:19], v[10:13]
	s_cbranch_vccnz .LBB0_1099
	s_andn2_b64 vcc, exec, s[6:7]
	s_cbranch_vccnz .LBB0_1098
	s_barrier
	s_branch .LBB0_1098
